# phase 1 row loop: x rows prefetched two row pairs ahead (three register sets) instead of one
# baseline (speedup 1.0000x reference)
.LBB0_171:
	global_load_dwordx4 v[144:147], v[28:29], off
	global_load_dwordx4 v[148:151], v[28:29], off offset:1024
	global_load_dwordx4 v[152:155], v[28:29], off offset:2048
	global_load_dwordx4 v[156:159], v[28:29], off offset:3072
	s_ashr_i32 s0, s4, 11
	s_mul_i32 s0, s0, 6
	s_lshl_b32 s0, s0, 12
	s_add_u32 s14, s90, s0
	s_addc_u32 s15, s91, 0
	s_add_u32 s16, s14, 0x1000
	s_addc_u32 s17, s15, 0
	global_load_dwordx4 v[160:163], v42, s[14:15]
	global_load_dwordx4 v[164:167], v42, s[14:15] offset:1024
	global_load_dwordx4 v[168:171], v42, s[14:15] offset:2048
	global_load_dwordx4 v[172:175], v42, s[14:15] offset:3072
	global_load_dwordx4 v[176:179], v42, s[16:17]
	global_load_dwordx4 v[180:183], v42, s[16:17] offset:1024
	global_load_dwordx4 v[184:187], v42, s[16:17] offset:2048
	global_load_dwordx4 v[188:191], v42, s[16:17] offset:3072
	global_load_dwordx4 v[48:51], v[32:33], off offset:-4096 nt
	global_load_dwordx4 v[52:55], v[32:33], off offset:-3072 nt
	global_load_dwordx4 v[56:59], v[32:33], off offset:-2048 nt
	global_load_dwordx4 v[60:63], v[32:33], off offset:-1024 nt
	global_load_dwordx4 v[64:67], v[32:33], off nt
	global_load_dwordx4 v[68:71], v[32:33], off offset:1024 nt
	global_load_dwordx4 v[72:75], v[32:33], off offset:2048 nt
	global_load_dwordx4 v[76:79], v[32:33], off offset:3072 nt
	s_add_i32 s5, s4, s8
	s_cmp_gt_i32 s5, s101
	s_cselect_b32 s0, 0, s12
	s_cselect_b32 s1, 0, s13
	v_lshl_add_u64 v[32:33], v[32:33], 0, s[0:1]
	global_load_dwordx4 v[80:83], v[32:33], off offset:-4096 nt
	global_load_dwordx4 v[84:87], v[32:33], off offset:-3072 nt
	global_load_dwordx4 v[88:91], v[32:33], off offset:-2048 nt
	global_load_dwordx4 v[92:95], v[32:33], off offset:-1024 nt
	global_load_dwordx4 v[96:99], v[32:33], off nt
	global_load_dwordx4 v[100:103], v[32:33], off offset:1024 nt
	global_load_dwordx4 v[104:107], v[32:33], off offset:2048 nt
	global_load_dwordx4 v[108:111], v[32:33], off offset:3072 nt
	s_waitcnt vmcnt(0)
.Lrms_loop:
	s_add_i32 s5, s4, s8
	s_min_i32 s0, s5, s101
	s_ashr_i32 s0, s0, 11
	s_mul_i32 s0, s0, 6
	s_lshl_b32 s0, s0, 12
	s_add_u32 s14, s90, s0
	s_addc_u32 s15, s91, 0
	s_add_u32 s16, s14, 0x1000
	s_addc_u32 s17, s15, 0
	global_load_dwordx4 v[194:197], v42, s[14:15]
	global_load_dwordx4 v[198:201], v42, s[14:15] offset:1024
	global_load_dwordx4 v[202:205], v42, s[14:15] offset:2048
	global_load_dwordx4 v[206:209], v42, s[14:15] offset:3072
	global_load_dwordx4 v[210:213], v42, s[16:17]
	global_load_dwordx4 v[214:217], v42, s[16:17] offset:1024
	global_load_dwordx4 v[218:221], v42, s[16:17] offset:2048
	global_load_dwordx4 v[222:225], v42, s[16:17] offset:3072
	s_add_i32 s5, s5, s8
	s_cmp_gt_i32 s5, s101
	s_cselect_b32 s0, 0, s12
	s_cselect_b32 s1, 0, s13
	v_lshl_add_u64 v[32:33], v[32:33], 0, s[0:1]
	global_load_dwordx4 v[112:115], v[32:33], off offset:-4096 nt
	global_load_dwordx4 v[116:119], v[32:33], off offset:-3072 nt
	global_load_dwordx4 v[120:123], v[32:33], off offset:-2048 nt
	global_load_dwordx4 v[124:127], v[32:33], off offset:-1024 nt
	global_load_dwordx4 v[128:131], v[32:33], off nt
	global_load_dwordx4 v[132:135], v[32:33], off offset:1024 nt
	global_load_dwordx4 v[136:139], v[32:33], off offset:2048 nt
	global_load_dwordx4 v[140:143], v[32:33], off offset:3072 nt
	s_waitcnt vmcnt(32)
	v_pk_mul_f32 v[0:1], v[48:49], v[48:49]
	v_pk_fma_f32 v[0:1], v[50:51], v[50:51], v[0:1]
	v_pk_fma_f32 v[0:1], v[52:53], v[52:53], v[0:1]
	v_pk_fma_f32 v[0:1], v[54:55], v[54:55], v[0:1]
	v_pk_fma_f32 v[0:1], v[56:57], v[56:57], v[0:1]
	v_pk_fma_f32 v[0:1], v[58:59], v[58:59], v[0:1]
	v_pk_fma_f32 v[0:1], v[60:61], v[60:61], v[0:1]
	v_pk_fma_f32 v[0:1], v[62:63], v[62:63], v[0:1]
	v_pk_mul_f32 v[2:3], v[64:65], v[64:65]
	v_pk_fma_f32 v[2:3], v[66:67], v[66:67], v[2:3]
	v_pk_fma_f32 v[2:3], v[68:69], v[68:69], v[2:3]
	v_pk_fma_f32 v[2:3], v[70:71], v[70:71], v[2:3]
	v_pk_fma_f32 v[2:3], v[72:73], v[72:73], v[2:3]
	v_pk_fma_f32 v[2:3], v[74:75], v[74:75], v[2:3]
	v_pk_fma_f32 v[2:3], v[76:77], v[76:77], v[2:3]
	v_pk_fma_f32 v[2:3], v[78:79], v[78:79], v[2:3]
	v_add_f32_e32 v0, v0, v1
	v_add_f32_e32 v2, v2, v3
	ds_bpermute_b32 v1, v34, v0
	ds_bpermute_b32 v3, v34, v2
	s_waitcnt lgkmcnt(0)
	v_add_f32_e32 v0, v0, v1
	v_add_f32_e32 v2, v2, v3
	ds_bpermute_b32 v1, v35, v0
	ds_bpermute_b32 v3, v35, v2
	s_waitcnt lgkmcnt(0)
	v_add_f32_e32 v0, v0, v1
	v_add_f32_e32 v2, v2, v3
	ds_bpermute_b32 v1, v36, v0
	ds_bpermute_b32 v3, v36, v2
	s_waitcnt lgkmcnt(0)
	v_add_f32_e32 v0, v0, v1
	v_add_f32_e32 v2, v2, v3
	ds_bpermute_b32 v1, v37, v0
	ds_bpermute_b32 v3, v37, v2
	s_waitcnt lgkmcnt(0)
	v_add_f32_e32 v0, v0, v1
	v_add_f32_e32 v2, v2, v3
	ds_bpermute_b32 v1, v38, v0
	ds_bpermute_b32 v3, v38, v2
	s_waitcnt lgkmcnt(0)
	v_add_f32_e32 v0, v0, v1
	v_add_f32_e32 v2, v2, v3
	ds_bpermute_b32 v1, v39, v0
	ds_bpermute_b32 v3, v39, v2
	s_waitcnt lgkmcnt(0)
	v_add_f32_e32 v0, v0, v1
	v_add_f32_e32 v2, v2, v3
	v_fmamk_f32 v0, v0, 0x3a800000, v40
	v_mul_f32_e32 v4, 0x4f800000, v0
	v_cmp_gt_f32_e32 vcc, s2, v0
	s_nop 1
	v_cndmask_b32_e32 v0, v0, v4, vcc
	v_sqrt_f32_e32 v4, v0
	s_nop 0
	v_add_u32_e32 v5, -1, v4
	v_add_u32_e32 v6, 1, v4
	v_fma_f32 v7, -v5, v4, v0
	v_fma_f32 v8, -v6, v4, v0
	v_cmp_ge_f32_e64 s[0:1], 0, v7
	s_nop 1
	v_cndmask_b32_e64 v4, v4, v5, s[0:1]
	v_cmp_lt_f32_e64 s[0:1], 0, v8
	s_nop 1
	v_cndmask_b32_e64 v4, v4, v6, s[0:1]
	v_mul_f32_e32 v5, 0x37800000, v4
	v_cndmask_b32_e32 v4, v4, v5, vcc
	v_cmp_class_f32_e32 vcc, v0, v41
	s_nop 1
	v_cndmask_b32_e32 v0, v4, v0, vcc
	v_div_scale_f32 v4, s[0:1], v0, v0, 1.0
	v_rcp_f32_e32 v6, v4
	v_div_scale_f32 v5, vcc, 1.0, v0, 1.0
	v_fma_f32 v7, -v4, v6, 1.0
	v_fmac_f32_e32 v6, v7, v6
	v_mul_f32_e32 v7, v5, v6
	v_fma_f32 v8, -v4, v7, v5
	v_fmac_f32_e32 v7, v8, v6
	v_fma_f32 v4, -v4, v7, v5
	v_div_fmas_f32 v4, v4, v6, v7
	v_div_fixup_f32 v0, v4, v0, 1.0
	v_fmamk_f32 v2, v2, 0x3a800000, v40
	v_mul_f32_e32 v10, 0x4f800000, v2
	v_cmp_gt_f32_e32 vcc, s2, v2
	s_nop 1
	v_cndmask_b32_e32 v2, v2, v10, vcc
	v_sqrt_f32_e32 v10, v2
	s_nop 0
	v_add_u32_e32 v11, -1, v10
	v_add_u32_e32 v12, 1, v10
	v_fma_f32 v13, -v11, v10, v2
	v_fma_f32 v14, -v12, v10, v2
	v_cmp_ge_f32_e64 s[0:1], 0, v13
	s_nop 1
	v_cndmask_b32_e64 v10, v10, v11, s[0:1]
	v_cmp_lt_f32_e64 s[0:1], 0, v14
	s_nop 1
	v_cndmask_b32_e64 v10, v10, v12, s[0:1]
	v_mul_f32_e32 v11, 0x37800000, v10
	v_cndmask_b32_e32 v10, v10, v11, vcc
	v_cmp_class_f32_e32 vcc, v2, v41
	s_nop 1
	v_cndmask_b32_e32 v2, v10, v2, vcc
	v_div_scale_f32 v10, s[0:1], v2, v2, 1.0
	v_rcp_f32_e32 v12, v10
	v_div_scale_f32 v11, vcc, 1.0, v2, 1.0
	v_fma_f32 v13, -v10, v12, 1.0
	v_fmac_f32_e32 v12, v13, v12
	v_mul_f32_e32 v13, v11, v12
	v_fma_f32 v14, -v10, v13, v11
	v_fmac_f32_e32 v13, v14, v12
	v_fma_f32 v10, -v10, v13, v11
	v_div_fmas_f32 v10, v10, v12, v13
	v_div_fixup_f32 v2, v10, v2, 1.0
	v_pk_add_f32 v[176:177], v[176:177], 1.0 op_sel_hi:[1,0]
	v_pk_add_f32 v[178:179], v[178:179], 1.0 op_sel_hi:[1,0]
	v_pk_add_f32 v[180:181], v[180:181], 1.0 op_sel_hi:[1,0]
	v_pk_add_f32 v[182:183], v[182:183], 1.0 op_sel_hi:[1,0]
	v_pk_add_f32 v[184:185], v[184:185], 1.0 op_sel_hi:[1,0]
	v_pk_add_f32 v[186:187], v[186:187], 1.0 op_sel_hi:[1,0]
	v_pk_add_f32 v[188:189], v[188:189], 1.0 op_sel_hi:[1,0]
	v_pk_add_f32 v[190:191], v[190:191], 1.0 op_sel_hi:[1,0]
	v_pk_mul_f32 v[48:49], v[48:49], v[0:1] op_sel_hi:[1,0]
	v_pk_mul_f32 v[50:51], v[50:51], v[0:1] op_sel_hi:[1,0]
	v_pk_mul_f32 v[48:49], v[144:145], v[48:49]
	v_pk_mul_f32 v[50:51], v[146:147], v[50:51]
	v_pk_fma_f32 v[48:49], v[176:177], v[48:49], v[160:161]
	v_pk_fma_f32 v[50:51], v[178:179], v[50:51], v[162:163]
	v_cvt_pk_bf16_f32 v48, v48, v49
	v_cvt_pk_bf16_f32 v49, v50, v51
	global_store_dwordx2 v[30:31], v[48:49], off offset:-3584
	v_pk_mul_f32 v[52:53], v[52:53], v[0:1] op_sel_hi:[1,0]
	v_pk_mul_f32 v[54:55], v[54:55], v[0:1] op_sel_hi:[1,0]
	v_pk_mul_f32 v[52:53], v[148:149], v[52:53]
	v_pk_mul_f32 v[54:55], v[150:151], v[54:55]
	v_pk_fma_f32 v[52:53], v[180:181], v[52:53], v[164:165]
	v_pk_fma_f32 v[54:55], v[182:183], v[54:55], v[166:167]
	v_cvt_pk_bf16_f32 v52, v52, v53
	v_cvt_pk_bf16_f32 v53, v54, v55
	global_store_dwordx2 v[30:31], v[52:53], off offset:-3072
	v_pk_mul_f32 v[56:57], v[56:57], v[0:1] op_sel_hi:[1,0]
	v_pk_mul_f32 v[58:59], v[58:59], v[0:1] op_sel_hi:[1,0]
	v_pk_mul_f32 v[56:57], v[152:153], v[56:57]
	v_pk_mul_f32 v[58:59], v[154:155], v[58:59]
	v_pk_fma_f32 v[56:57], v[184:185], v[56:57], v[168:169]
	v_pk_fma_f32 v[58:59], v[186:187], v[58:59], v[170:171]
	v_cvt_pk_bf16_f32 v56, v56, v57
	v_cvt_pk_bf16_f32 v57, v58, v59
	global_store_dwordx2 v[30:31], v[56:57], off offset:-2560
	v_pk_mul_f32 v[60:61], v[60:61], v[0:1] op_sel_hi:[1,0]
	v_pk_mul_f32 v[62:63], v[62:63], v[0:1] op_sel_hi:[1,0]
	v_pk_mul_f32 v[60:61], v[156:157], v[60:61]
	v_pk_mul_f32 v[62:63], v[158:159], v[62:63]
	v_pk_fma_f32 v[60:61], v[188:189], v[60:61], v[172:173]
	v_pk_fma_f32 v[62:63], v[190:191], v[62:63], v[174:175]
	v_cvt_pk_bf16_f32 v60, v60, v61
	v_cvt_pk_bf16_f32 v61, v62, v63
	global_store_dwordx2 v[30:31], v[60:61], off offset:-2048
	v_pk_mul_f32 v[64:65], v[64:65], v[2:3] op_sel_hi:[1,0]
	v_pk_mul_f32 v[66:67], v[66:67], v[2:3] op_sel_hi:[1,0]
	v_pk_mul_f32 v[64:65], v[144:145], v[64:65]
	v_pk_mul_f32 v[66:67], v[146:147], v[66:67]
	v_pk_fma_f32 v[64:65], v[176:177], v[64:65], v[160:161]
	v_pk_fma_f32 v[66:67], v[178:179], v[66:67], v[162:163]
	v_cvt_pk_bf16_f32 v64, v64, v65
	v_cvt_pk_bf16_f32 v65, v66, v67
	global_store_dwordx2 v[30:31], v[64:65], off offset:-1536
	v_pk_mul_f32 v[68:69], v[68:69], v[2:3] op_sel_hi:[1,0]
	v_pk_mul_f32 v[70:71], v[70:71], v[2:3] op_sel_hi:[1,0]
	v_pk_mul_f32 v[68:69], v[148:149], v[68:69]
	v_pk_mul_f32 v[70:71], v[150:151], v[70:71]
	v_pk_fma_f32 v[68:69], v[180:181], v[68:69], v[164:165]
	v_pk_fma_f32 v[70:71], v[182:183], v[70:71], v[166:167]
	v_cvt_pk_bf16_f32 v68, v68, v69
	v_cvt_pk_bf16_f32 v69, v70, v71
	global_store_dwordx2 v[30:31], v[68:69], off offset:-1024
	v_pk_mul_f32 v[72:73], v[72:73], v[2:3] op_sel_hi:[1,0]
	v_pk_mul_f32 v[74:75], v[74:75], v[2:3] op_sel_hi:[1,0]
	v_pk_mul_f32 v[72:73], v[152:153], v[72:73]
	v_pk_mul_f32 v[74:75], v[154:155], v[74:75]
	v_pk_fma_f32 v[72:73], v[184:185], v[72:73], v[168:169]
	v_pk_fma_f32 v[74:75], v[186:187], v[74:75], v[170:171]
	v_cvt_pk_bf16_f32 v72, v72, v73
	v_cvt_pk_bf16_f32 v73, v74, v75
	global_store_dwordx2 v[30:31], v[72:73], off offset:-512
	v_pk_mul_f32 v[76:77], v[76:77], v[2:3] op_sel_hi:[1,0]
	v_pk_mul_f32 v[78:79], v[78:79], v[2:3] op_sel_hi:[1,0]
	v_pk_mul_f32 v[76:77], v[156:157], v[76:77]
	v_pk_mul_f32 v[78:79], v[158:159], v[78:79]
	v_pk_fma_f32 v[76:77], v[188:189], v[76:77], v[172:173]
	v_pk_fma_f32 v[78:79], v[190:191], v[78:79], v[174:175]
	v_cvt_pk_bf16_f32 v76, v76, v77
	v_cvt_pk_bf16_f32 v77, v78, v79
	global_store_dwordx2 v[30:31], v[76:77], off
	v_lshl_add_u64 v[30:31], v[30:31], 0, s[10:11]
	s_add_i32 s4, s4, s8
	s_cmp_gt_i32 s4, s101
	s_cbranch_scc1 .Lrms_exit
	s_add_i32 s5, s4, s8
	s_min_i32 s0, s5, s101
	s_ashr_i32 s0, s0, 11
	s_mul_i32 s0, s0, 6
	s_lshl_b32 s0, s0, 12
	s_add_u32 s14, s90, s0
	s_addc_u32 s15, s91, 0
	s_add_u32 s16, s14, 0x1000
	s_addc_u32 s17, s15, 0
	global_load_dwordx4 v[160:163], v42, s[14:15]
	global_load_dwordx4 v[164:167], v42, s[14:15] offset:1024
	global_load_dwordx4 v[168:171], v42, s[14:15] offset:2048
	global_load_dwordx4 v[172:175], v42, s[14:15] offset:3072
	global_load_dwordx4 v[176:179], v42, s[16:17]
	global_load_dwordx4 v[180:183], v42, s[16:17] offset:1024
	global_load_dwordx4 v[184:187], v42, s[16:17] offset:2048
	global_load_dwordx4 v[188:191], v42, s[16:17] offset:3072
	s_add_i32 s5, s5, s8
	s_cmp_gt_i32 s5, s101
	s_cselect_b32 s0, 0, s12
	s_cselect_b32 s1, 0, s13
	v_lshl_add_u64 v[32:33], v[32:33], 0, s[0:1]
	global_load_dwordx4 v[48:51], v[32:33], off offset:-4096 nt
	global_load_dwordx4 v[52:55], v[32:33], off offset:-3072 nt
	global_load_dwordx4 v[56:59], v[32:33], off offset:-2048 nt
	global_load_dwordx4 v[60:63], v[32:33], off offset:-1024 nt
	global_load_dwordx4 v[64:67], v[32:33], off nt
	global_load_dwordx4 v[68:71], v[32:33], off offset:1024 nt
	global_load_dwordx4 v[72:75], v[32:33], off offset:2048 nt
	global_load_dwordx4 v[76:79], v[32:33], off offset:3072 nt
	s_waitcnt vmcnt(32)
	v_pk_mul_f32 v[0:1], v[80:81], v[80:81]
	v_pk_fma_f32 v[0:1], v[82:83], v[82:83], v[0:1]
	v_pk_fma_f32 v[0:1], v[84:85], v[84:85], v[0:1]
	v_pk_fma_f32 v[0:1], v[86:87], v[86:87], v[0:1]
	v_pk_fma_f32 v[0:1], v[88:89], v[88:89], v[0:1]
	v_pk_fma_f32 v[0:1], v[90:91], v[90:91], v[0:1]
	v_pk_fma_f32 v[0:1], v[92:93], v[92:93], v[0:1]
	v_pk_fma_f32 v[0:1], v[94:95], v[94:95], v[0:1]
	v_pk_mul_f32 v[2:3], v[96:97], v[96:97]
	v_pk_fma_f32 v[2:3], v[98:99], v[98:99], v[2:3]
	v_pk_fma_f32 v[2:3], v[100:101], v[100:101], v[2:3]
	v_pk_fma_f32 v[2:3], v[102:103], v[102:103], v[2:3]
	v_pk_fma_f32 v[2:3], v[104:105], v[104:105], v[2:3]
	v_pk_fma_f32 v[2:3], v[106:107], v[106:107], v[2:3]
	v_pk_fma_f32 v[2:3], v[108:109], v[108:109], v[2:3]
	v_pk_fma_f32 v[2:3], v[110:111], v[110:111], v[2:3]
	v_add_f32_e32 v0, v0, v1
	v_add_f32_e32 v2, v2, v3
	ds_bpermute_b32 v1, v34, v0
	ds_bpermute_b32 v3, v34, v2
	s_waitcnt lgkmcnt(0)
	v_add_f32_e32 v0, v0, v1
	v_add_f32_e32 v2, v2, v3
	ds_bpermute_b32 v1, v35, v0
	ds_bpermute_b32 v3, v35, v2
	s_waitcnt lgkmcnt(0)
	v_add_f32_e32 v0, v0, v1
	v_add_f32_e32 v2, v2, v3
	ds_bpermute_b32 v1, v36, v0
	ds_bpermute_b32 v3, v36, v2
	s_waitcnt lgkmcnt(0)
	v_add_f32_e32 v0, v0, v1
	v_add_f32_e32 v2, v2, v3
	ds_bpermute_b32 v1, v37, v0
	ds_bpermute_b32 v3, v37, v2
	s_waitcnt lgkmcnt(0)
	v_add_f32_e32 v0, v0, v1
	v_add_f32_e32 v2, v2, v3
	ds_bpermute_b32 v1, v38, v0
	ds_bpermute_b32 v3, v38, v2
	s_waitcnt lgkmcnt(0)
	v_add_f32_e32 v0, v0, v1
	v_add_f32_e32 v2, v2, v3
	ds_bpermute_b32 v1, v39, v0
	ds_bpermute_b32 v3, v39, v2
	s_waitcnt lgkmcnt(0)
	v_add_f32_e32 v0, v0, v1
	v_add_f32_e32 v2, v2, v3
	v_fmamk_f32 v0, v0, 0x3a800000, v40
	v_mul_f32_e32 v4, 0x4f800000, v0
	v_cmp_gt_f32_e32 vcc, s2, v0
	s_nop 1
	v_cndmask_b32_e32 v0, v0, v4, vcc
	v_sqrt_f32_e32 v4, v0
	s_nop 0
	v_add_u32_e32 v5, -1, v4
	v_add_u32_e32 v6, 1, v4
	v_fma_f32 v7, -v5, v4, v0
	v_fma_f32 v8, -v6, v4, v0
	v_cmp_ge_f32_e64 s[0:1], 0, v7
	s_nop 1
	v_cndmask_b32_e64 v4, v4, v5, s[0:1]
	v_cmp_lt_f32_e64 s[0:1], 0, v8
	s_nop 1
	v_cndmask_b32_e64 v4, v4, v6, s[0:1]
	v_mul_f32_e32 v5, 0x37800000, v4
	v_cndmask_b32_e32 v4, v4, v5, vcc
	v_cmp_class_f32_e32 vcc, v0, v41
	s_nop 1
	v_cndmask_b32_e32 v0, v4, v0, vcc
	v_div_scale_f32 v4, s[0:1], v0, v0, 1.0
	v_rcp_f32_e32 v6, v4
	v_div_scale_f32 v5, vcc, 1.0, v0, 1.0
	v_fma_f32 v7, -v4, v6, 1.0
	v_fmac_f32_e32 v6, v7, v6
	v_mul_f32_e32 v7, v5, v6
	v_fma_f32 v8, -v4, v7, v5
	v_fmac_f32_e32 v7, v8, v6
	v_fma_f32 v4, -v4, v7, v5
	v_div_fmas_f32 v4, v4, v6, v7
	v_div_fixup_f32 v0, v4, v0, 1.0
	v_fmamk_f32 v2, v2, 0x3a800000, v40
	v_mul_f32_e32 v10, 0x4f800000, v2
	v_cmp_gt_f32_e32 vcc, s2, v2
	s_nop 1
	v_cndmask_b32_e32 v2, v2, v10, vcc
	v_sqrt_f32_e32 v10, v2
	s_nop 0
	v_add_u32_e32 v11, -1, v10
	v_add_u32_e32 v12, 1, v10
	v_fma_f32 v13, -v11, v10, v2
	v_fma_f32 v14, -v12, v10, v2
	v_cmp_ge_f32_e64 s[0:1], 0, v13
	s_nop 1
	v_cndmask_b32_e64 v10, v10, v11, s[0:1]
	v_cmp_lt_f32_e64 s[0:1], 0, v14
	s_nop 1
	v_cndmask_b32_e64 v10, v10, v12, s[0:1]
	v_mul_f32_e32 v11, 0x37800000, v10
	v_cndmask_b32_e32 v10, v10, v11, vcc
	v_cmp_class_f32_e32 vcc, v2, v41
	s_nop 1
	v_cndmask_b32_e32 v2, v10, v2, vcc
	v_div_scale_f32 v10, s[0:1], v2, v2, 1.0
	v_rcp_f32_e32 v12, v10
	v_div_scale_f32 v11, vcc, 1.0, v2, 1.0
	v_fma_f32 v13, -v10, v12, 1.0
	v_fmac_f32_e32 v12, v13, v12
	v_mul_f32_e32 v13, v11, v12
	v_fma_f32 v14, -v10, v13, v11
	v_fmac_f32_e32 v13, v14, v12
	v_fma_f32 v10, -v10, v13, v11
	v_div_fmas_f32 v10, v10, v12, v13
	v_div_fixup_f32 v2, v10, v2, 1.0
	v_pk_add_f32 v[210:211], v[210:211], 1.0 op_sel_hi:[1,0]
	v_pk_add_f32 v[212:213], v[212:213], 1.0 op_sel_hi:[1,0]
	v_pk_add_f32 v[214:215], v[214:215], 1.0 op_sel_hi:[1,0]
	v_pk_add_f32 v[216:217], v[216:217], 1.0 op_sel_hi:[1,0]
	v_pk_add_f32 v[218:219], v[218:219], 1.0 op_sel_hi:[1,0]
	v_pk_add_f32 v[220:221], v[220:221], 1.0 op_sel_hi:[1,0]
	v_pk_add_f32 v[222:223], v[222:223], 1.0 op_sel_hi:[1,0]
	v_pk_add_f32 v[224:225], v[224:225], 1.0 op_sel_hi:[1,0]
	v_pk_mul_f32 v[80:81], v[80:81], v[0:1] op_sel_hi:[1,0]
	v_pk_mul_f32 v[82:83], v[82:83], v[0:1] op_sel_hi:[1,0]
	v_pk_mul_f32 v[80:81], v[144:145], v[80:81]
	v_pk_mul_f32 v[82:83], v[146:147], v[82:83]
	v_pk_fma_f32 v[80:81], v[210:211], v[80:81], v[194:195]
	v_pk_fma_f32 v[82:83], v[212:213], v[82:83], v[196:197]
	v_cvt_pk_bf16_f32 v80, v80, v81
	v_cvt_pk_bf16_f32 v81, v82, v83
	global_store_dwordx2 v[30:31], v[80:81], off offset:-3584
	v_pk_mul_f32 v[84:85], v[84:85], v[0:1] op_sel_hi:[1,0]
	v_pk_mul_f32 v[86:87], v[86:87], v[0:1] op_sel_hi:[1,0]
	v_pk_mul_f32 v[84:85], v[148:149], v[84:85]
	v_pk_mul_f32 v[86:87], v[150:151], v[86:87]
	v_pk_fma_f32 v[84:85], v[214:215], v[84:85], v[198:199]
	v_pk_fma_f32 v[86:87], v[216:217], v[86:87], v[200:201]
	v_cvt_pk_bf16_f32 v84, v84, v85
	v_cvt_pk_bf16_f32 v85, v86, v87
	global_store_dwordx2 v[30:31], v[84:85], off offset:-3072
	v_pk_mul_f32 v[88:89], v[88:89], v[0:1] op_sel_hi:[1,0]
	v_pk_mul_f32 v[90:91], v[90:91], v[0:1] op_sel_hi:[1,0]
	v_pk_mul_f32 v[88:89], v[152:153], v[88:89]
	v_pk_mul_f32 v[90:91], v[154:155], v[90:91]
	v_pk_fma_f32 v[88:89], v[218:219], v[88:89], v[202:203]
	v_pk_fma_f32 v[90:91], v[220:221], v[90:91], v[204:205]
	v_cvt_pk_bf16_f32 v88, v88, v89
	v_cvt_pk_bf16_f32 v89, v90, v91
	global_store_dwordx2 v[30:31], v[88:89], off offset:-2560
	v_pk_mul_f32 v[92:93], v[92:93], v[0:1] op_sel_hi:[1,0]
	v_pk_mul_f32 v[94:95], v[94:95], v[0:1] op_sel_hi:[1,0]
	v_pk_mul_f32 v[92:93], v[156:157], v[92:93]
	v_pk_mul_f32 v[94:95], v[158:159], v[94:95]
	v_pk_fma_f32 v[92:93], v[222:223], v[92:93], v[206:207]
	v_pk_fma_f32 v[94:95], v[224:225], v[94:95], v[208:209]
	v_cvt_pk_bf16_f32 v92, v92, v93
	v_cvt_pk_bf16_f32 v93, v94, v95
	global_store_dwordx2 v[30:31], v[92:93], off offset:-2048
	v_pk_mul_f32 v[96:97], v[96:97], v[2:3] op_sel_hi:[1,0]
	v_pk_mul_f32 v[98:99], v[98:99], v[2:3] op_sel_hi:[1,0]
	v_pk_mul_f32 v[96:97], v[144:145], v[96:97]
	v_pk_mul_f32 v[98:99], v[146:147], v[98:99]
	v_pk_fma_f32 v[96:97], v[210:211], v[96:97], v[194:195]
	v_pk_fma_f32 v[98:99], v[212:213], v[98:99], v[196:197]
	v_cvt_pk_bf16_f32 v96, v96, v97
	v_cvt_pk_bf16_f32 v97, v98, v99
	global_store_dwordx2 v[30:31], v[96:97], off offset:-1536
	v_pk_mul_f32 v[100:101], v[100:101], v[2:3] op_sel_hi:[1,0]
	v_pk_mul_f32 v[102:103], v[102:103], v[2:3] op_sel_hi:[1,0]
	v_pk_mul_f32 v[100:101], v[148:149], v[100:101]
	v_pk_mul_f32 v[102:103], v[150:151], v[102:103]
	v_pk_fma_f32 v[100:101], v[214:215], v[100:101], v[198:199]
	v_pk_fma_f32 v[102:103], v[216:217], v[102:103], v[200:201]
	v_cvt_pk_bf16_f32 v100, v100, v101
	v_cvt_pk_bf16_f32 v101, v102, v103
	global_store_dwordx2 v[30:31], v[100:101], off offset:-1024
	v_pk_mul_f32 v[104:105], v[104:105], v[2:3] op_sel_hi:[1,0]
	v_pk_mul_f32 v[106:107], v[106:107], v[2:3] op_sel_hi:[1,0]
	v_pk_mul_f32 v[104:105], v[152:153], v[104:105]
	v_pk_mul_f32 v[106:107], v[154:155], v[106:107]
	v_pk_fma_f32 v[104:105], v[218:219], v[104:105], v[202:203]
	v_pk_fma_f32 v[106:107], v[220:221], v[106:107], v[204:205]
	v_cvt_pk_bf16_f32 v104, v104, v105
	v_cvt_pk_bf16_f32 v105, v106, v107
	global_store_dwordx2 v[30:31], v[104:105], off offset:-512
	v_pk_mul_f32 v[108:109], v[108:109], v[2:3] op_sel_hi:[1,0]
	v_pk_mul_f32 v[110:111], v[110:111], v[2:3] op_sel_hi:[1,0]
	v_pk_mul_f32 v[108:109], v[156:157], v[108:109]
	v_pk_mul_f32 v[110:111], v[158:159], v[110:111]
	v_pk_fma_f32 v[108:109], v[222:223], v[108:109], v[206:207]
	v_pk_fma_f32 v[110:111], v[224:225], v[110:111], v[208:209]
	v_cvt_pk_bf16_f32 v108, v108, v109
	v_cvt_pk_bf16_f32 v109, v110, v111
	global_store_dwordx2 v[30:31], v[108:109], off
	v_lshl_add_u64 v[30:31], v[30:31], 0, s[10:11]
	s_add_i32 s4, s4, s8
	s_cmp_gt_i32 s4, s101
	s_cbranch_scc1 .Lrms_exit
	s_add_i32 s5, s4, s8
	s_min_i32 s0, s5, s101
	s_ashr_i32 s0, s0, 11
	s_mul_i32 s0, s0, 6
	s_lshl_b32 s0, s0, 12
	s_add_u32 s14, s90, s0
	s_addc_u32 s15, s91, 0
	s_add_u32 s16, s14, 0x1000
	s_addc_u32 s17, s15, 0
	global_load_dwordx4 v[194:197], v42, s[14:15]
	global_load_dwordx4 v[198:201], v42, s[14:15] offset:1024
	global_load_dwordx4 v[202:205], v42, s[14:15] offset:2048
	global_load_dwordx4 v[206:209], v42, s[14:15] offset:3072
	global_load_dwordx4 v[210:213], v42, s[16:17]
	global_load_dwordx4 v[214:217], v42, s[16:17] offset:1024
	global_load_dwordx4 v[218:221], v42, s[16:17] offset:2048
	global_load_dwordx4 v[222:225], v42, s[16:17] offset:3072
	s_add_i32 s5, s5, s8
	s_cmp_gt_i32 s5, s101
	s_cselect_b32 s0, 0, s12
	s_cselect_b32 s1, 0, s13
	v_lshl_add_u64 v[32:33], v[32:33], 0, s[0:1]
	global_load_dwordx4 v[80:83], v[32:33], off offset:-4096 nt
	global_load_dwordx4 v[84:87], v[32:33], off offset:-3072 nt
	global_load_dwordx4 v[88:91], v[32:33], off offset:-2048 nt
	global_load_dwordx4 v[92:95], v[32:33], off offset:-1024 nt
	global_load_dwordx4 v[96:99], v[32:33], off nt
	global_load_dwordx4 v[100:103], v[32:33], off offset:1024 nt
	global_load_dwordx4 v[104:107], v[32:33], off offset:2048 nt
	global_load_dwordx4 v[108:111], v[32:33], off offset:3072 nt
	s_waitcnt vmcnt(32)
	v_pk_mul_f32 v[0:1], v[112:113], v[112:113]
	v_pk_fma_f32 v[0:1], v[114:115], v[114:115], v[0:1]
	v_pk_fma_f32 v[0:1], v[116:117], v[116:117], v[0:1]
	v_pk_fma_f32 v[0:1], v[118:119], v[118:119], v[0:1]
	v_pk_fma_f32 v[0:1], v[120:121], v[120:121], v[0:1]
	v_pk_fma_f32 v[0:1], v[122:123], v[122:123], v[0:1]
	v_pk_fma_f32 v[0:1], v[124:125], v[124:125], v[0:1]
	v_pk_fma_f32 v[0:1], v[126:127], v[126:127], v[0:1]
	v_pk_mul_f32 v[2:3], v[128:129], v[128:129]
	v_pk_fma_f32 v[2:3], v[130:131], v[130:131], v[2:3]
	v_pk_fma_f32 v[2:3], v[132:133], v[132:133], v[2:3]
	v_pk_fma_f32 v[2:3], v[134:135], v[134:135], v[2:3]
	v_pk_fma_f32 v[2:3], v[136:137], v[136:137], v[2:3]
	v_pk_fma_f32 v[2:3], v[138:139], v[138:139], v[2:3]
	v_pk_fma_f32 v[2:3], v[140:141], v[140:141], v[2:3]
	v_pk_fma_f32 v[2:3], v[142:143], v[142:143], v[2:3]
	v_add_f32_e32 v0, v0, v1
	v_add_f32_e32 v2, v2, v3
	ds_bpermute_b32 v1, v34, v0
	ds_bpermute_b32 v3, v34, v2
	s_waitcnt lgkmcnt(0)
	v_add_f32_e32 v0, v0, v1
	v_add_f32_e32 v2, v2, v3
	ds_bpermute_b32 v1, v35, v0
	ds_bpermute_b32 v3, v35, v2
	s_waitcnt lgkmcnt(0)
	v_add_f32_e32 v0, v0, v1
	v_add_f32_e32 v2, v2, v3
	ds_bpermute_b32 v1, v36, v0
	ds_bpermute_b32 v3, v36, v2
	s_waitcnt lgkmcnt(0)
	v_add_f32_e32 v0, v0, v1
	v_add_f32_e32 v2, v2, v3
	ds_bpermute_b32 v1, v37, v0
	ds_bpermute_b32 v3, v37, v2
	s_waitcnt lgkmcnt(0)
	v_add_f32_e32 v0, v0, v1
	v_add_f32_e32 v2, v2, v3
	ds_bpermute_b32 v1, v38, v0
	ds_bpermute_b32 v3, v38, v2
	s_waitcnt lgkmcnt(0)
	v_add_f32_e32 v0, v0, v1
	v_add_f32_e32 v2, v2, v3
	ds_bpermute_b32 v1, v39, v0
	ds_bpermute_b32 v3, v39, v2
	s_waitcnt lgkmcnt(0)
	v_add_f32_e32 v0, v0, v1
	v_add_f32_e32 v2, v2, v3
	v_fmamk_f32 v0, v0, 0x3a800000, v40
	v_mul_f32_e32 v4, 0x4f800000, v0
	v_cmp_gt_f32_e32 vcc, s2, v0
	s_nop 1
	v_cndmask_b32_e32 v0, v0, v4, vcc
	v_sqrt_f32_e32 v4, v0
	s_nop 0
	v_add_u32_e32 v5, -1, v4
	v_add_u32_e32 v6, 1, v4
	v_fma_f32 v7, -v5, v4, v0
	v_fma_f32 v8, -v6, v4, v0
	v_cmp_ge_f32_e64 s[0:1], 0, v7
	s_nop 1
	v_cndmask_b32_e64 v4, v4, v5, s[0:1]
	v_cmp_lt_f32_e64 s[0:1], 0, v8
	s_nop 1
	v_cndmask_b32_e64 v4, v4, v6, s[0:1]
	v_mul_f32_e32 v5, 0x37800000, v4
	v_cndmask_b32_e32 v4, v4, v5, vcc
	v_cmp_class_f32_e32 vcc, v0, v41
	s_nop 1
	v_cndmask_b32_e32 v0, v4, v0, vcc
	v_div_scale_f32 v4, s[0:1], v0, v0, 1.0
	v_rcp_f32_e32 v6, v4
	v_div_scale_f32 v5, vcc, 1.0, v0, 1.0
	v_fma_f32 v7, -v4, v6, 1.0
	v_fmac_f32_e32 v6, v7, v6
	v_mul_f32_e32 v7, v5, v6
	v_fma_f32 v8, -v4, v7, v5
	v_fmac_f32_e32 v7, v8, v6
	v_fma_f32 v4, -v4, v7, v5
	v_div_fmas_f32 v4, v4, v6, v7
	v_div_fixup_f32 v0, v4, v0, 1.0
	v_fmamk_f32 v2, v2, 0x3a800000, v40
	v_mul_f32_e32 v10, 0x4f800000, v2
	v_cmp_gt_f32_e32 vcc, s2, v2
	s_nop 1
	v_cndmask_b32_e32 v2, v2, v10, vcc
	v_sqrt_f32_e32 v10, v2
	s_nop 0
	v_add_u32_e32 v11, -1, v10
	v_add_u32_e32 v12, 1, v10
	v_fma_f32 v13, -v11, v10, v2
	v_fma_f32 v14, -v12, v10, v2
	v_cmp_ge_f32_e64 s[0:1], 0, v13
	s_nop 1
	v_cndmask_b32_e64 v10, v10, v11, s[0:1]
	v_cmp_lt_f32_e64 s[0:1], 0, v14
	s_nop 1
	v_cndmask_b32_e64 v10, v10, v12, s[0:1]
	v_mul_f32_e32 v11, 0x37800000, v10
	v_cndmask_b32_e32 v10, v10, v11, vcc
	v_cmp_class_f32_e32 vcc, v2, v41
	s_nop 1
	v_cndmask_b32_e32 v2, v10, v2, vcc
	v_div_scale_f32 v10, s[0:1], v2, v2, 1.0
	v_rcp_f32_e32 v12, v10
	v_div_scale_f32 v11, vcc, 1.0, v2, 1.0
	v_fma_f32 v13, -v10, v12, 1.0
	v_fmac_f32_e32 v12, v13, v12
	v_mul_f32_e32 v13, v11, v12
	v_fma_f32 v14, -v10, v13, v11
	v_fmac_f32_e32 v13, v14, v12
	v_fma_f32 v10, -v10, v13, v11
	v_div_fmas_f32 v10, v10, v12, v13
	v_div_fixup_f32 v2, v10, v2, 1.0
	v_pk_add_f32 v[176:177], v[176:177], 1.0 op_sel_hi:[1,0]
	v_pk_add_f32 v[178:179], v[178:179], 1.0 op_sel_hi:[1,0]
	v_pk_add_f32 v[180:181], v[180:181], 1.0 op_sel_hi:[1,0]
	v_pk_add_f32 v[182:183], v[182:183], 1.0 op_sel_hi:[1,0]
	v_pk_add_f32 v[184:185], v[184:185], 1.0 op_sel_hi:[1,0]
	v_pk_add_f32 v[186:187], v[186:187], 1.0 op_sel_hi:[1,0]
	v_pk_add_f32 v[188:189], v[188:189], 1.0 op_sel_hi:[1,0]
	v_pk_add_f32 v[190:191], v[190:191], 1.0 op_sel_hi:[1,0]
	v_pk_mul_f32 v[112:113], v[112:113], v[0:1] op_sel_hi:[1,0]
	v_pk_mul_f32 v[114:115], v[114:115], v[0:1] op_sel_hi:[1,0]
	v_pk_mul_f32 v[112:113], v[144:145], v[112:113]
	v_pk_mul_f32 v[114:115], v[146:147], v[114:115]
	v_pk_fma_f32 v[112:113], v[176:177], v[112:113], v[160:161]
	v_pk_fma_f32 v[114:115], v[178:179], v[114:115], v[162:163]
	v_cvt_pk_bf16_f32 v112, v112, v113
	v_cvt_pk_bf16_f32 v113, v114, v115
	global_store_dwordx2 v[30:31], v[112:113], off offset:-3584
	v_pk_mul_f32 v[116:117], v[116:117], v[0:1] op_sel_hi:[1,0]
	v_pk_mul_f32 v[118:119], v[118:119], v[0:1] op_sel_hi:[1,0]
	v_pk_mul_f32 v[116:117], v[148:149], v[116:117]
	v_pk_mul_f32 v[118:119], v[150:151], v[118:119]
	v_pk_fma_f32 v[116:117], v[180:181], v[116:117], v[164:165]
	v_pk_fma_f32 v[118:119], v[182:183], v[118:119], v[166:167]
	v_cvt_pk_bf16_f32 v116, v116, v117
	v_cvt_pk_bf16_f32 v117, v118, v119
	global_store_dwordx2 v[30:31], v[116:117], off offset:-3072
	v_pk_mul_f32 v[120:121], v[120:121], v[0:1] op_sel_hi:[1,0]
	v_pk_mul_f32 v[122:123], v[122:123], v[0:1] op_sel_hi:[1,0]
	v_pk_mul_f32 v[120:121], v[152:153], v[120:121]
	v_pk_mul_f32 v[122:123], v[154:155], v[122:123]
	v_pk_fma_f32 v[120:121], v[184:185], v[120:121], v[168:169]
	v_pk_fma_f32 v[122:123], v[186:187], v[122:123], v[170:171]
	v_cvt_pk_bf16_f32 v120, v120, v121
	v_cvt_pk_bf16_f32 v121, v122, v123
	global_store_dwordx2 v[30:31], v[120:121], off offset:-2560
	v_pk_mul_f32 v[124:125], v[124:125], v[0:1] op_sel_hi:[1,0]
	v_pk_mul_f32 v[126:127], v[126:127], v[0:1] op_sel_hi:[1,0]
	v_pk_mul_f32 v[124:125], v[156:157], v[124:125]
	v_pk_mul_f32 v[126:127], v[158:159], v[126:127]
	v_pk_fma_f32 v[124:125], v[188:189], v[124:125], v[172:173]
	v_pk_fma_f32 v[126:127], v[190:191], v[126:127], v[174:175]
	v_cvt_pk_bf16_f32 v124, v124, v125
	v_cvt_pk_bf16_f32 v125, v126, v127
	global_store_dwordx2 v[30:31], v[124:125], off offset:-2048
	v_pk_mul_f32 v[128:129], v[128:129], v[2:3] op_sel_hi:[1,0]
	v_pk_mul_f32 v[130:131], v[130:131], v[2:3] op_sel_hi:[1,0]
	v_pk_mul_f32 v[128:129], v[144:145], v[128:129]
	v_pk_mul_f32 v[130:131], v[146:147], v[130:131]
	v_pk_fma_f32 v[128:129], v[176:177], v[128:129], v[160:161]
	v_pk_fma_f32 v[130:131], v[178:179], v[130:131], v[162:163]
	v_cvt_pk_bf16_f32 v128, v128, v129
	v_cvt_pk_bf16_f32 v129, v130, v131
	global_store_dwordx2 v[30:31], v[128:129], off offset:-1536
	v_pk_mul_f32 v[132:133], v[132:133], v[2:3] op_sel_hi:[1,0]
	v_pk_mul_f32 v[134:135], v[134:135], v[2:3] op_sel_hi:[1,0]
	v_pk_mul_f32 v[132:133], v[148:149], v[132:133]
	v_pk_mul_f32 v[134:135], v[150:151], v[134:135]
	v_pk_fma_f32 v[132:133], v[180:181], v[132:133], v[164:165]
	v_pk_fma_f32 v[134:135], v[182:183], v[134:135], v[166:167]
	v_cvt_pk_bf16_f32 v132, v132, v133
	v_cvt_pk_bf16_f32 v133, v134, v135
	global_store_dwordx2 v[30:31], v[132:133], off offset:-1024
	v_pk_mul_f32 v[136:137], v[136:137], v[2:3] op_sel_hi:[1,0]
	v_pk_mul_f32 v[138:139], v[138:139], v[2:3] op_sel_hi:[1,0]
	v_pk_mul_f32 v[136:137], v[152:153], v[136:137]
	v_pk_mul_f32 v[138:139], v[154:155], v[138:139]
	v_pk_fma_f32 v[136:137], v[184:185], v[136:137], v[168:169]
	v_pk_fma_f32 v[138:139], v[186:187], v[138:139], v[170:171]
	v_cvt_pk_bf16_f32 v136, v136, v137
	v_cvt_pk_bf16_f32 v137, v138, v139
	global_store_dwordx2 v[30:31], v[136:137], off offset:-512
	v_pk_mul_f32 v[140:141], v[140:141], v[2:3] op_sel_hi:[1,0]
	v_pk_mul_f32 v[142:143], v[142:143], v[2:3] op_sel_hi:[1,0]
	v_pk_mul_f32 v[140:141], v[156:157], v[140:141]
	v_pk_mul_f32 v[142:143], v[158:159], v[142:143]
	v_pk_fma_f32 v[140:141], v[188:189], v[140:141], v[172:173]
	v_pk_fma_f32 v[142:143], v[190:191], v[142:143], v[174:175]
	v_cvt_pk_bf16_f32 v140, v140, v141
	v_cvt_pk_bf16_f32 v141, v142, v143
	global_store_dwordx2 v[30:31], v[140:141], off
	v_lshl_add_u64 v[30:31], v[30:31], 0, s[10:11]
	s_add_i32 s4, s4, s8
	s_cmp_gt_i32 s4, s101
	s_cbranch_scc1 .Lrms_exit
	s_add_i32 s5, s4, s8
	s_min_i32 s0, s5, s101
	s_ashr_i32 s0, s0, 11
	s_mul_i32 s0, s0, 6
	s_lshl_b32 s0, s0, 12
	s_add_u32 s14, s90, s0
	s_addc_u32 s15, s91, 0
	s_add_u32 s16, s14, 0x1000
	s_addc_u32 s17, s15, 0
	global_load_dwordx4 v[160:163], v42, s[14:15]
	global_load_dwordx4 v[164:167], v42, s[14:15] offset:1024
	global_load_dwordx4 v[168:171], v42, s[14:15] offset:2048
	global_load_dwordx4 v[172:175], v42, s[14:15] offset:3072
	global_load_dwordx4 v[176:179], v42, s[16:17]
	global_load_dwordx4 v[180:183], v42, s[16:17] offset:1024
	global_load_dwordx4 v[184:187], v42, s[16:17] offset:2048
	global_load_dwordx4 v[188:191], v42, s[16:17] offset:3072
	s_add_i32 s5, s5, s8
	s_cmp_gt_i32 s5, s101
	s_cselect_b32 s0, 0, s12
	s_cselect_b32 s1, 0, s13
	v_lshl_add_u64 v[32:33], v[32:33], 0, s[0:1]
	global_load_dwordx4 v[112:115], v[32:33], off offset:-4096 nt
	global_load_dwordx4 v[116:119], v[32:33], off offset:-3072 nt
	global_load_dwordx4 v[120:123], v[32:33], off offset:-2048 nt
	global_load_dwordx4 v[124:127], v[32:33], off offset:-1024 nt
	global_load_dwordx4 v[128:131], v[32:33], off nt
	global_load_dwordx4 v[132:135], v[32:33], off offset:1024 nt
	global_load_dwordx4 v[136:139], v[32:33], off offset:2048 nt
	global_load_dwordx4 v[140:143], v[32:33], off offset:3072 nt
	s_waitcnt vmcnt(32)
	v_pk_mul_f32 v[0:1], v[48:49], v[48:49]
	v_pk_fma_f32 v[0:1], v[50:51], v[50:51], v[0:1]
	v_pk_fma_f32 v[0:1], v[52:53], v[52:53], v[0:1]
	v_pk_fma_f32 v[0:1], v[54:55], v[54:55], v[0:1]
	v_pk_fma_f32 v[0:1], v[56:57], v[56:57], v[0:1]
	v_pk_fma_f32 v[0:1], v[58:59], v[58:59], v[0:1]
	v_pk_fma_f32 v[0:1], v[60:61], v[60:61], v[0:1]
	v_pk_fma_f32 v[0:1], v[62:63], v[62:63], v[0:1]
	v_pk_mul_f32 v[2:3], v[64:65], v[64:65]
	v_pk_fma_f32 v[2:3], v[66:67], v[66:67], v[2:3]
	v_pk_fma_f32 v[2:3], v[68:69], v[68:69], v[2:3]
	v_pk_fma_f32 v[2:3], v[70:71], v[70:71], v[2:3]
	v_pk_fma_f32 v[2:3], v[72:73], v[72:73], v[2:3]
	v_pk_fma_f32 v[2:3], v[74:75], v[74:75], v[2:3]
	v_pk_fma_f32 v[2:3], v[76:77], v[76:77], v[2:3]
	v_pk_fma_f32 v[2:3], v[78:79], v[78:79], v[2:3]
	v_add_f32_e32 v0, v0, v1
	v_add_f32_e32 v2, v2, v3
	ds_bpermute_b32 v1, v34, v0
	ds_bpermute_b32 v3, v34, v2
	s_waitcnt lgkmcnt(0)
	v_add_f32_e32 v0, v0, v1
	v_add_f32_e32 v2, v2, v3
	ds_bpermute_b32 v1, v35, v0
	ds_bpermute_b32 v3, v35, v2
	s_waitcnt lgkmcnt(0)
	v_add_f32_e32 v0, v0, v1
	v_add_f32_e32 v2, v2, v3
	ds_bpermute_b32 v1, v36, v0
	ds_bpermute_b32 v3, v36, v2
	s_waitcnt lgkmcnt(0)
	v_add_f32_e32 v0, v0, v1
	v_add_f32_e32 v2, v2, v3
	ds_bpermute_b32 v1, v37, v0
	ds_bpermute_b32 v3, v37, v2
	s_waitcnt lgkmcnt(0)
	v_add_f32_e32 v0, v0, v1
	v_add_f32_e32 v2, v2, v3
	ds_bpermute_b32 v1, v38, v0
	ds_bpermute_b32 v3, v38, v2
	s_waitcnt lgkmcnt(0)
	v_add_f32_e32 v0, v0, v1
	v_add_f32_e32 v2, v2, v3
	ds_bpermute_b32 v1, v39, v0
	ds_bpermute_b32 v3, v39, v2
	s_waitcnt lgkmcnt(0)
	v_add_f32_e32 v0, v0, v1
	v_add_f32_e32 v2, v2, v3
	v_fmamk_f32 v0, v0, 0x3a800000, v40
	v_mul_f32_e32 v4, 0x4f800000, v0
	v_cmp_gt_f32_e32 vcc, s2, v0
	s_nop 1
	v_cndmask_b32_e32 v0, v0, v4, vcc
	v_sqrt_f32_e32 v4, v0
	s_nop 0
	v_add_u32_e32 v5, -1, v4
	v_add_u32_e32 v6, 1, v4
	v_fma_f32 v7, -v5, v4, v0
	v_fma_f32 v8, -v6, v4, v0
	v_cmp_ge_f32_e64 s[0:1], 0, v7
	s_nop 1
	v_cndmask_b32_e64 v4, v4, v5, s[0:1]
	v_cmp_lt_f32_e64 s[0:1], 0, v8
	s_nop 1
	v_cndmask_b32_e64 v4, v4, v6, s[0:1]
	v_mul_f32_e32 v5, 0x37800000, v4
	v_cndmask_b32_e32 v4, v4, v5, vcc
	v_cmp_class_f32_e32 vcc, v0, v41
	s_nop 1
	v_cndmask_b32_e32 v0, v4, v0, vcc
	v_div_scale_f32 v4, s[0:1], v0, v0, 1.0
	v_rcp_f32_e32 v6, v4
	v_div_scale_f32 v5, vcc, 1.0, v0, 1.0
	v_fma_f32 v7, -v4, v6, 1.0
	v_fmac_f32_e32 v6, v7, v6
	v_mul_f32_e32 v7, v5, v6
	v_fma_f32 v8, -v4, v7, v5
	v_fmac_f32_e32 v7, v8, v6
	v_fma_f32 v4, -v4, v7, v5
	v_div_fmas_f32 v4, v4, v6, v7
	v_div_fixup_f32 v0, v4, v0, 1.0
	v_fmamk_f32 v2, v2, 0x3a800000, v40
	v_mul_f32_e32 v10, 0x4f800000, v2
	v_cmp_gt_f32_e32 vcc, s2, v2
	s_nop 1
	v_cndmask_b32_e32 v2, v2, v10, vcc
	v_sqrt_f32_e32 v10, v2
	s_nop 0
	v_add_u32_e32 v11, -1, v10
	v_add_u32_e32 v12, 1, v10
	v_fma_f32 v13, -v11, v10, v2
	v_fma_f32 v14, -v12, v10, v2
	v_cmp_ge_f32_e64 s[0:1], 0, v13
	s_nop 1
	v_cndmask_b32_e64 v10, v10, v11, s[0:1]
	v_cmp_lt_f32_e64 s[0:1], 0, v14
	s_nop 1
	v_cndmask_b32_e64 v10, v10, v12, s[0:1]
	v_mul_f32_e32 v11, 0x37800000, v10
	v_cndmask_b32_e32 v10, v10, v11, vcc
	v_cmp_class_f32_e32 vcc, v2, v41
	s_nop 1
	v_cndmask_b32_e32 v2, v10, v2, vcc
	v_div_scale_f32 v10, s[0:1], v2, v2, 1.0
	v_rcp_f32_e32 v12, v10
	v_div_scale_f32 v11, vcc, 1.0, v2, 1.0
	v_fma_f32 v13, -v10, v12, 1.0
	v_fmac_f32_e32 v12, v13, v12
	v_mul_f32_e32 v13, v11, v12
	v_fma_f32 v14, -v10, v13, v11
	v_fmac_f32_e32 v13, v14, v12
	v_fma_f32 v10, -v10, v13, v11
	v_div_fmas_f32 v10, v10, v12, v13
	v_div_fixup_f32 v2, v10, v2, 1.0
	v_pk_add_f32 v[210:211], v[210:211], 1.0 op_sel_hi:[1,0]
	v_pk_add_f32 v[212:213], v[212:213], 1.0 op_sel_hi:[1,0]
	v_pk_add_f32 v[214:215], v[214:215], 1.0 op_sel_hi:[1,0]
	v_pk_add_f32 v[216:217], v[216:217], 1.0 op_sel_hi:[1,0]
	v_pk_add_f32 v[218:219], v[218:219], 1.0 op_sel_hi:[1,0]
	v_pk_add_f32 v[220:221], v[220:221], 1.0 op_sel_hi:[1,0]
	v_pk_add_f32 v[222:223], v[222:223], 1.0 op_sel_hi:[1,0]
	v_pk_add_f32 v[224:225], v[224:225], 1.0 op_sel_hi:[1,0]
	v_pk_mul_f32 v[48:49], v[48:49], v[0:1] op_sel_hi:[1,0]
	v_pk_mul_f32 v[50:51], v[50:51], v[0:1] op_sel_hi:[1,0]
	v_pk_mul_f32 v[48:49], v[144:145], v[48:49]
	v_pk_mul_f32 v[50:51], v[146:147], v[50:51]
	v_pk_fma_f32 v[48:49], v[210:211], v[48:49], v[194:195]
	v_pk_fma_f32 v[50:51], v[212:213], v[50:51], v[196:197]
	v_cvt_pk_bf16_f32 v48, v48, v49
	v_cvt_pk_bf16_f32 v49, v50, v51
	global_store_dwordx2 v[30:31], v[48:49], off offset:-3584
	v_pk_mul_f32 v[52:53], v[52:53], v[0:1] op_sel_hi:[1,0]
	v_pk_mul_f32 v[54:55], v[54:55], v[0:1] op_sel_hi:[1,0]
	v_pk_mul_f32 v[52:53], v[148:149], v[52:53]
	v_pk_mul_f32 v[54:55], v[150:151], v[54:55]
	v_pk_fma_f32 v[52:53], v[214:215], v[52:53], v[198:199]
	v_pk_fma_f32 v[54:55], v[216:217], v[54:55], v[200:201]
	v_cvt_pk_bf16_f32 v52, v52, v53
	v_cvt_pk_bf16_f32 v53, v54, v55
	global_store_dwordx2 v[30:31], v[52:53], off offset:-3072
	v_pk_mul_f32 v[56:57], v[56:57], v[0:1] op_sel_hi:[1,0]
	v_pk_mul_f32 v[58:59], v[58:59], v[0:1] op_sel_hi:[1,0]
	v_pk_mul_f32 v[56:57], v[152:153], v[56:57]
	v_pk_mul_f32 v[58:59], v[154:155], v[58:59]
	v_pk_fma_f32 v[56:57], v[218:219], v[56:57], v[202:203]
	v_pk_fma_f32 v[58:59], v[220:221], v[58:59], v[204:205]
	v_cvt_pk_bf16_f32 v56, v56, v57
	v_cvt_pk_bf16_f32 v57, v58, v59
	global_store_dwordx2 v[30:31], v[56:57], off offset:-2560
	v_pk_mul_f32 v[60:61], v[60:61], v[0:1] op_sel_hi:[1,0]
	v_pk_mul_f32 v[62:63], v[62:63], v[0:1] op_sel_hi:[1,0]
	v_pk_mul_f32 v[60:61], v[156:157], v[60:61]
	v_pk_mul_f32 v[62:63], v[158:159], v[62:63]
	v_pk_fma_f32 v[60:61], v[222:223], v[60:61], v[206:207]
	v_pk_fma_f32 v[62:63], v[224:225], v[62:63], v[208:209]
	v_cvt_pk_bf16_f32 v60, v60, v61
	v_cvt_pk_bf16_f32 v61, v62, v63
	global_store_dwordx2 v[30:31], v[60:61], off offset:-2048
	v_pk_mul_f32 v[64:65], v[64:65], v[2:3] op_sel_hi:[1,0]
	v_pk_mul_f32 v[66:67], v[66:67], v[2:3] op_sel_hi:[1,0]
	v_pk_mul_f32 v[64:65], v[144:145], v[64:65]
	v_pk_mul_f32 v[66:67], v[146:147], v[66:67]
	v_pk_fma_f32 v[64:65], v[210:211], v[64:65], v[194:195]
	v_pk_fma_f32 v[66:67], v[212:213], v[66:67], v[196:197]
	v_cvt_pk_bf16_f32 v64, v64, v65
	v_cvt_pk_bf16_f32 v65, v66, v67
	global_store_dwordx2 v[30:31], v[64:65], off offset:-1536
	v_pk_mul_f32 v[68:69], v[68:69], v[2:3] op_sel_hi:[1,0]
	v_pk_mul_f32 v[70:71], v[70:71], v[2:3] op_sel_hi:[1,0]
	v_pk_mul_f32 v[68:69], v[148:149], v[68:69]
	v_pk_mul_f32 v[70:71], v[150:151], v[70:71]
	v_pk_fma_f32 v[68:69], v[214:215], v[68:69], v[198:199]
	v_pk_fma_f32 v[70:71], v[216:217], v[70:71], v[200:201]
	v_cvt_pk_bf16_f32 v68, v68, v69
	v_cvt_pk_bf16_f32 v69, v70, v71
	global_store_dwordx2 v[30:31], v[68:69], off offset:-1024
	v_pk_mul_f32 v[72:73], v[72:73], v[2:3] op_sel_hi:[1,0]
	v_pk_mul_f32 v[74:75], v[74:75], v[2:3] op_sel_hi:[1,0]
	v_pk_mul_f32 v[72:73], v[152:153], v[72:73]
	v_pk_mul_f32 v[74:75], v[154:155], v[74:75]
	v_pk_fma_f32 v[72:73], v[218:219], v[72:73], v[202:203]
	v_pk_fma_f32 v[74:75], v[220:221], v[74:75], v[204:205]
	v_cvt_pk_bf16_f32 v72, v72, v73
	v_cvt_pk_bf16_f32 v73, v74, v75
	global_store_dwordx2 v[30:31], v[72:73], off offset:-512
	v_pk_mul_f32 v[76:77], v[76:77], v[2:3] op_sel_hi:[1,0]
	v_pk_mul_f32 v[78:79], v[78:79], v[2:3] op_sel_hi:[1,0]
	v_pk_mul_f32 v[76:77], v[156:157], v[76:77]
	v_pk_mul_f32 v[78:79], v[158:159], v[78:79]
	v_pk_fma_f32 v[76:77], v[222:223], v[76:77], v[206:207]
	v_pk_fma_f32 v[78:79], v[224:225], v[78:79], v[208:209]
	v_cvt_pk_bf16_f32 v76, v76, v77
	v_cvt_pk_bf16_f32 v77, v78, v79
	global_store_dwordx2 v[30:31], v[76:77], off
	v_lshl_add_u64 v[30:31], v[30:31], 0, s[10:11]
	s_add_i32 s4, s4, s8
	s_cmp_gt_i32 s4, s101
	s_cbranch_scc1 .Lrms_exit
	s_add_i32 s5, s4, s8
	s_min_i32 s0, s5, s101
	s_ashr_i32 s0, s0, 11
	s_mul_i32 s0, s0, 6
	s_lshl_b32 s0, s0, 12
	s_add_u32 s14, s90, s0
	s_addc_u32 s15, s91, 0
	s_add_u32 s16, s14, 0x1000
	s_addc_u32 s17, s15, 0
	global_load_dwordx4 v[194:197], v42, s[14:15]
	global_load_dwordx4 v[198:201], v42, s[14:15] offset:1024
	global_load_dwordx4 v[202:205], v42, s[14:15] offset:2048
	global_load_dwordx4 v[206:209], v42, s[14:15] offset:3072
	global_load_dwordx4 v[210:213], v42, s[16:17]
	global_load_dwordx4 v[214:217], v42, s[16:17] offset:1024
	global_load_dwordx4 v[218:221], v42, s[16:17] offset:2048
	global_load_dwordx4 v[222:225], v42, s[16:17] offset:3072
	s_add_i32 s5, s5, s8
	s_cmp_gt_i32 s5, s101
	s_cselect_b32 s0, 0, s12
	s_cselect_b32 s1, 0, s13
	v_lshl_add_u64 v[32:33], v[32:33], 0, s[0:1]
	global_load_dwordx4 v[48:51], v[32:33], off offset:-4096 nt
	global_load_dwordx4 v[52:55], v[32:33], off offset:-3072 nt
	global_load_dwordx4 v[56:59], v[32:33], off offset:-2048 nt
	global_load_dwordx4 v[60:63], v[32:33], off offset:-1024 nt
	global_load_dwordx4 v[64:67], v[32:33], off nt
	global_load_dwordx4 v[68:71], v[32:33], off offset:1024 nt
	global_load_dwordx4 v[72:75], v[32:33], off offset:2048 nt
	global_load_dwordx4 v[76:79], v[32:33], off offset:3072 nt
	s_waitcnt vmcnt(32)
	v_pk_mul_f32 v[0:1], v[80:81], v[80:81]
	v_pk_fma_f32 v[0:1], v[82:83], v[82:83], v[0:1]
	v_pk_fma_f32 v[0:1], v[84:85], v[84:85], v[0:1]
	v_pk_fma_f32 v[0:1], v[86:87], v[86:87], v[0:1]
	v_pk_fma_f32 v[0:1], v[88:89], v[88:89], v[0:1]
	v_pk_fma_f32 v[0:1], v[90:91], v[90:91], v[0:1]
	v_pk_fma_f32 v[0:1], v[92:93], v[92:93], v[0:1]
	v_pk_fma_f32 v[0:1], v[94:95], v[94:95], v[0:1]
	v_pk_mul_f32 v[2:3], v[96:97], v[96:97]
	v_pk_fma_f32 v[2:3], v[98:99], v[98:99], v[2:3]
	v_pk_fma_f32 v[2:3], v[100:101], v[100:101], v[2:3]
	v_pk_fma_f32 v[2:3], v[102:103], v[102:103], v[2:3]
	v_pk_fma_f32 v[2:3], v[104:105], v[104:105], v[2:3]
	v_pk_fma_f32 v[2:3], v[106:107], v[106:107], v[2:3]
	v_pk_fma_f32 v[2:3], v[108:109], v[108:109], v[2:3]
	v_pk_fma_f32 v[2:3], v[110:111], v[110:111], v[2:3]
	v_add_f32_e32 v0, v0, v1
	v_add_f32_e32 v2, v2, v3
	ds_bpermute_b32 v1, v34, v0
	ds_bpermute_b32 v3, v34, v2
	s_waitcnt lgkmcnt(0)
	v_add_f32_e32 v0, v0, v1
	v_add_f32_e32 v2, v2, v3
	ds_bpermute_b32 v1, v35, v0
	ds_bpermute_b32 v3, v35, v2
	s_waitcnt lgkmcnt(0)
	v_add_f32_e32 v0, v0, v1
	v_add_f32_e32 v2, v2, v3
	ds_bpermute_b32 v1, v36, v0
	ds_bpermute_b32 v3, v36, v2
	s_waitcnt lgkmcnt(0)
	v_add_f32_e32 v0, v0, v1
	v_add_f32_e32 v2, v2, v3
	ds_bpermute_b32 v1, v37, v0
	ds_bpermute_b32 v3, v37, v2
	s_waitcnt lgkmcnt(0)
	v_add_f32_e32 v0, v0, v1
	v_add_f32_e32 v2, v2, v3
	ds_bpermute_b32 v1, v38, v0
	ds_bpermute_b32 v3, v38, v2
	s_waitcnt lgkmcnt(0)
	v_add_f32_e32 v0, v0, v1
	v_add_f32_e32 v2, v2, v3
	ds_bpermute_b32 v1, v39, v0
	ds_bpermute_b32 v3, v39, v2
	s_waitcnt lgkmcnt(0)
	v_add_f32_e32 v0, v0, v1
	v_add_f32_e32 v2, v2, v3
	v_fmamk_f32 v0, v0, 0x3a800000, v40
	v_mul_f32_e32 v4, 0x4f800000, v0
	v_cmp_gt_f32_e32 vcc, s2, v0
	s_nop 1
	v_cndmask_b32_e32 v0, v0, v4, vcc
	v_sqrt_f32_e32 v4, v0
	s_nop 0
	v_add_u32_e32 v5, -1, v4
	v_add_u32_e32 v6, 1, v4
	v_fma_f32 v7, -v5, v4, v0
	v_fma_f32 v8, -v6, v4, v0
	v_cmp_ge_f32_e64 s[0:1], 0, v7
	s_nop 1
	v_cndmask_b32_e64 v4, v4, v5, s[0:1]
	v_cmp_lt_f32_e64 s[0:1], 0, v8
	s_nop 1
	v_cndmask_b32_e64 v4, v4, v6, s[0:1]
	v_mul_f32_e32 v5, 0x37800000, v4
	v_cndmask_b32_e32 v4, v4, v5, vcc
	v_cmp_class_f32_e32 vcc, v0, v41
	s_nop 1
	v_cndmask_b32_e32 v0, v4, v0, vcc
	v_div_scale_f32 v4, s[0:1], v0, v0, 1.0
	v_rcp_f32_e32 v6, v4
	v_div_scale_f32 v5, vcc, 1.0, v0, 1.0
	v_fma_f32 v7, -v4, v6, 1.0
	v_fmac_f32_e32 v6, v7, v6
	v_mul_f32_e32 v7, v5, v6
	v_fma_f32 v8, -v4, v7, v5
	v_fmac_f32_e32 v7, v8, v6
	v_fma_f32 v4, -v4, v7, v5
	v_div_fmas_f32 v4, v4, v6, v7
	v_div_fixup_f32 v0, v4, v0, 1.0
	v_fmamk_f32 v2, v2, 0x3a800000, v40
	v_mul_f32_e32 v10, 0x4f800000, v2
	v_cmp_gt_f32_e32 vcc, s2, v2
	s_nop 1
	v_cndmask_b32_e32 v2, v2, v10, vcc
	v_sqrt_f32_e32 v10, v2
	s_nop 0
	v_add_u32_e32 v11, -1, v10
	v_add_u32_e32 v12, 1, v10
	v_fma_f32 v13, -v11, v10, v2
	v_fma_f32 v14, -v12, v10, v2
	v_cmp_ge_f32_e64 s[0:1], 0, v13
	s_nop 1
	v_cndmask_b32_e64 v10, v10, v11, s[0:1]
	v_cmp_lt_f32_e64 s[0:1], 0, v14
	s_nop 1
	v_cndmask_b32_e64 v10, v10, v12, s[0:1]
	v_mul_f32_e32 v11, 0x37800000, v10
	v_cndmask_b32_e32 v10, v10, v11, vcc
	v_cmp_class_f32_e32 vcc, v2, v41
	s_nop 1
	v_cndmask_b32_e32 v2, v10, v2, vcc
	v_div_scale_f32 v10, s[0:1], v2, v2, 1.0
	v_rcp_f32_e32 v12, v10
	v_div_scale_f32 v11, vcc, 1.0, v2, 1.0
	v_fma_f32 v13, -v10, v12, 1.0
	v_fmac_f32_e32 v12, v13, v12
	v_mul_f32_e32 v13, v11, v12
	v_fma_f32 v14, -v10, v13, v11
	v_fmac_f32_e32 v13, v14, v12
	v_fma_f32 v10, -v10, v13, v11
	v_div_fmas_f32 v10, v10, v12, v13
	v_div_fixup_f32 v2, v10, v2, 1.0
	v_pk_add_f32 v[176:177], v[176:177], 1.0 op_sel_hi:[1,0]
	v_pk_add_f32 v[178:179], v[178:179], 1.0 op_sel_hi:[1,0]
	v_pk_add_f32 v[180:181], v[180:181], 1.0 op_sel_hi:[1,0]
	v_pk_add_f32 v[182:183], v[182:183], 1.0 op_sel_hi:[1,0]
	v_pk_add_f32 v[184:185], v[184:185], 1.0 op_sel_hi:[1,0]
	v_pk_add_f32 v[186:187], v[186:187], 1.0 op_sel_hi:[1,0]
	v_pk_add_f32 v[188:189], v[188:189], 1.0 op_sel_hi:[1,0]
	v_pk_add_f32 v[190:191], v[190:191], 1.0 op_sel_hi:[1,0]
	v_pk_mul_f32 v[80:81], v[80:81], v[0:1] op_sel_hi:[1,0]
	v_pk_mul_f32 v[82:83], v[82:83], v[0:1] op_sel_hi:[1,0]
	v_pk_mul_f32 v[80:81], v[144:145], v[80:81]
	v_pk_mul_f32 v[82:83], v[146:147], v[82:83]
	v_pk_fma_f32 v[80:81], v[176:177], v[80:81], v[160:161]
	v_pk_fma_f32 v[82:83], v[178:179], v[82:83], v[162:163]
	v_cvt_pk_bf16_f32 v80, v80, v81
	v_cvt_pk_bf16_f32 v81, v82, v83
	global_store_dwordx2 v[30:31], v[80:81], off offset:-3584
	v_pk_mul_f32 v[84:85], v[84:85], v[0:1] op_sel_hi:[1,0]
	v_pk_mul_f32 v[86:87], v[86:87], v[0:1] op_sel_hi:[1,0]
	v_pk_mul_f32 v[84:85], v[148:149], v[84:85]
	v_pk_mul_f32 v[86:87], v[150:151], v[86:87]
	v_pk_fma_f32 v[84:85], v[180:181], v[84:85], v[164:165]
	v_pk_fma_f32 v[86:87], v[182:183], v[86:87], v[166:167]
	v_cvt_pk_bf16_f32 v84, v84, v85
	v_cvt_pk_bf16_f32 v85, v86, v87
	global_store_dwordx2 v[30:31], v[84:85], off offset:-3072
	v_pk_mul_f32 v[88:89], v[88:89], v[0:1] op_sel_hi:[1,0]
	v_pk_mul_f32 v[90:91], v[90:91], v[0:1] op_sel_hi:[1,0]
	v_pk_mul_f32 v[88:89], v[152:153], v[88:89]
	v_pk_mul_f32 v[90:91], v[154:155], v[90:91]
	v_pk_fma_f32 v[88:89], v[184:185], v[88:89], v[168:169]
	v_pk_fma_f32 v[90:91], v[186:187], v[90:91], v[170:171]
	v_cvt_pk_bf16_f32 v88, v88, v89
	v_cvt_pk_bf16_f32 v89, v90, v91
	global_store_dwordx2 v[30:31], v[88:89], off offset:-2560
	v_pk_mul_f32 v[92:93], v[92:93], v[0:1] op_sel_hi:[1,0]
	v_pk_mul_f32 v[94:95], v[94:95], v[0:1] op_sel_hi:[1,0]
	v_pk_mul_f32 v[92:93], v[156:157], v[92:93]
	v_pk_mul_f32 v[94:95], v[158:159], v[94:95]
	v_pk_fma_f32 v[92:93], v[188:189], v[92:93], v[172:173]
	v_pk_fma_f32 v[94:95], v[190:191], v[94:95], v[174:175]
	v_cvt_pk_bf16_f32 v92, v92, v93
	v_cvt_pk_bf16_f32 v93, v94, v95
	global_store_dwordx2 v[30:31], v[92:93], off offset:-2048
	v_pk_mul_f32 v[96:97], v[96:97], v[2:3] op_sel_hi:[1,0]
	v_pk_mul_f32 v[98:99], v[98:99], v[2:3] op_sel_hi:[1,0]
	v_pk_mul_f32 v[96:97], v[144:145], v[96:97]
	v_pk_mul_f32 v[98:99], v[146:147], v[98:99]
	v_pk_fma_f32 v[96:97], v[176:177], v[96:97], v[160:161]
	v_pk_fma_f32 v[98:99], v[178:179], v[98:99], v[162:163]
	v_cvt_pk_bf16_f32 v96, v96, v97
	v_cvt_pk_bf16_f32 v97, v98, v99
	global_store_dwordx2 v[30:31], v[96:97], off offset:-1536
	v_pk_mul_f32 v[100:101], v[100:101], v[2:3] op_sel_hi:[1,0]
	v_pk_mul_f32 v[102:103], v[102:103], v[2:3] op_sel_hi:[1,0]
	v_pk_mul_f32 v[100:101], v[148:149], v[100:101]
	v_pk_mul_f32 v[102:103], v[150:151], v[102:103]
	v_pk_fma_f32 v[100:101], v[180:181], v[100:101], v[164:165]
	v_pk_fma_f32 v[102:103], v[182:183], v[102:103], v[166:167]
	v_cvt_pk_bf16_f32 v100, v100, v101
	v_cvt_pk_bf16_f32 v101, v102, v103
	global_store_dwordx2 v[30:31], v[100:101], off offset:-1024
	v_pk_mul_f32 v[104:105], v[104:105], v[2:3] op_sel_hi:[1,0]
	v_pk_mul_f32 v[106:107], v[106:107], v[2:3] op_sel_hi:[1,0]
	v_pk_mul_f32 v[104:105], v[152:153], v[104:105]
	v_pk_mul_f32 v[106:107], v[154:155], v[106:107]
	v_pk_fma_f32 v[104:105], v[184:185], v[104:105], v[168:169]
	v_pk_fma_f32 v[106:107], v[186:187], v[106:107], v[170:171]
	v_cvt_pk_bf16_f32 v104, v104, v105
	v_cvt_pk_bf16_f32 v105, v106, v107
	global_store_dwordx2 v[30:31], v[104:105], off offset:-512
	v_pk_mul_f32 v[108:109], v[108:109], v[2:3] op_sel_hi:[1,0]
	v_pk_mul_f32 v[110:111], v[110:111], v[2:3] op_sel_hi:[1,0]
	v_pk_mul_f32 v[108:109], v[156:157], v[108:109]
	v_pk_mul_f32 v[110:111], v[158:159], v[110:111]
	v_pk_fma_f32 v[108:109], v[188:189], v[108:109], v[172:173]
	v_pk_fma_f32 v[110:111], v[190:191], v[110:111], v[174:175]
	v_cvt_pk_bf16_f32 v108, v108, v109
	v_cvt_pk_bf16_f32 v109, v110, v111
	global_store_dwordx2 v[30:31], v[108:109], off
	v_lshl_add_u64 v[30:31], v[30:31], 0, s[10:11]
	s_add_i32 s4, s4, s8
	s_cmp_gt_i32 s4, s101
	s_cbranch_scc1 .Lrms_exit
	s_add_i32 s5, s4, s8
	s_min_i32 s0, s5, s101
	s_ashr_i32 s0, s0, 11
	s_mul_i32 s0, s0, 6
	s_lshl_b32 s0, s0, 12
	s_add_u32 s14, s90, s0
	s_addc_u32 s15, s91, 0
	s_add_u32 s16, s14, 0x1000
	s_addc_u32 s17, s15, 0
	global_load_dwordx4 v[160:163], v42, s[14:15]
	global_load_dwordx4 v[164:167], v42, s[14:15] offset:1024
	global_load_dwordx4 v[168:171], v42, s[14:15] offset:2048
	global_load_dwordx4 v[172:175], v42, s[14:15] offset:3072
	global_load_dwordx4 v[176:179], v42, s[16:17]
	global_load_dwordx4 v[180:183], v42, s[16:17] offset:1024
	global_load_dwordx4 v[184:187], v42, s[16:17] offset:2048
	global_load_dwordx4 v[188:191], v42, s[16:17] offset:3072
	s_add_i32 s5, s5, s8
	s_cmp_gt_i32 s5, s101
	s_cselect_b32 s0, 0, s12
	s_cselect_b32 s1, 0, s13
	v_lshl_add_u64 v[32:33], v[32:33], 0, s[0:1]
	global_load_dwordx4 v[80:83], v[32:33], off offset:-4096 nt
	global_load_dwordx4 v[84:87], v[32:33], off offset:-3072 nt
	global_load_dwordx4 v[88:91], v[32:33], off offset:-2048 nt
	global_load_dwordx4 v[92:95], v[32:33], off offset:-1024 nt
	global_load_dwordx4 v[96:99], v[32:33], off nt
	global_load_dwordx4 v[100:103], v[32:33], off offset:1024 nt
	global_load_dwordx4 v[104:107], v[32:33], off offset:2048 nt
	global_load_dwordx4 v[108:111], v[32:33], off offset:3072 nt
	s_waitcnt vmcnt(32)
	v_pk_mul_f32 v[0:1], v[112:113], v[112:113]
	v_pk_fma_f32 v[0:1], v[114:115], v[114:115], v[0:1]
	v_pk_fma_f32 v[0:1], v[116:117], v[116:117], v[0:1]
	v_pk_fma_f32 v[0:1], v[118:119], v[118:119], v[0:1]
	v_pk_fma_f32 v[0:1], v[120:121], v[120:121], v[0:1]
	v_pk_fma_f32 v[0:1], v[122:123], v[122:123], v[0:1]
	v_pk_fma_f32 v[0:1], v[124:125], v[124:125], v[0:1]
	v_pk_fma_f32 v[0:1], v[126:127], v[126:127], v[0:1]
	v_pk_mul_f32 v[2:3], v[128:129], v[128:129]
	v_pk_fma_f32 v[2:3], v[130:131], v[130:131], v[2:3]
	v_pk_fma_f32 v[2:3], v[132:133], v[132:133], v[2:3]
	v_pk_fma_f32 v[2:3], v[134:135], v[134:135], v[2:3]
	v_pk_fma_f32 v[2:3], v[136:137], v[136:137], v[2:3]
	v_pk_fma_f32 v[2:3], v[138:139], v[138:139], v[2:3]
	v_pk_fma_f32 v[2:3], v[140:141], v[140:141], v[2:3]
	v_pk_fma_f32 v[2:3], v[142:143], v[142:143], v[2:3]
	v_add_f32_e32 v0, v0, v1
	v_add_f32_e32 v2, v2, v3
	ds_bpermute_b32 v1, v34, v0
	ds_bpermute_b32 v3, v34, v2
	s_waitcnt lgkmcnt(0)
	v_add_f32_e32 v0, v0, v1
	v_add_f32_e32 v2, v2, v3
	ds_bpermute_b32 v1, v35, v0
	ds_bpermute_b32 v3, v35, v2
	s_waitcnt lgkmcnt(0)
	v_add_f32_e32 v0, v0, v1
	v_add_f32_e32 v2, v2, v3
	ds_bpermute_b32 v1, v36, v0
	ds_bpermute_b32 v3, v36, v2
	s_waitcnt lgkmcnt(0)
	v_add_f32_e32 v0, v0, v1
	v_add_f32_e32 v2, v2, v3
	ds_bpermute_b32 v1, v37, v0
	ds_bpermute_b32 v3, v37, v2
	s_waitcnt lgkmcnt(0)
	v_add_f32_e32 v0, v0, v1
	v_add_f32_e32 v2, v2, v3
	ds_bpermute_b32 v1, v38, v0
	ds_bpermute_b32 v3, v38, v2
	s_waitcnt lgkmcnt(0)
	v_add_f32_e32 v0, v0, v1
	v_add_f32_e32 v2, v2, v3
	ds_bpermute_b32 v1, v39, v0
	ds_bpermute_b32 v3, v39, v2
	s_waitcnt lgkmcnt(0)
	v_add_f32_e32 v0, v0, v1
	v_add_f32_e32 v2, v2, v3
	v_fmamk_f32 v0, v0, 0x3a800000, v40
	v_mul_f32_e32 v4, 0x4f800000, v0
	v_cmp_gt_f32_e32 vcc, s2, v0
	s_nop 1
	v_cndmask_b32_e32 v0, v0, v4, vcc
	v_sqrt_f32_e32 v4, v0
	s_nop 0
	v_add_u32_e32 v5, -1, v4
	v_add_u32_e32 v6, 1, v4
	v_fma_f32 v7, -v5, v4, v0
	v_fma_f32 v8, -v6, v4, v0
	v_cmp_ge_f32_e64 s[0:1], 0, v7
	s_nop 1
	v_cndmask_b32_e64 v4, v4, v5, s[0:1]
	v_cmp_lt_f32_e64 s[0:1], 0, v8
	s_nop 1
	v_cndmask_b32_e64 v4, v4, v6, s[0:1]
	v_mul_f32_e32 v5, 0x37800000, v4
	v_cndmask_b32_e32 v4, v4, v5, vcc
	v_cmp_class_f32_e32 vcc, v0, v41
	s_nop 1
	v_cndmask_b32_e32 v0, v4, v0, vcc
	v_div_scale_f32 v4, s[0:1], v0, v0, 1.0
	v_rcp_f32_e32 v6, v4
	v_div_scale_f32 v5, vcc, 1.0, v0, 1.0
	v_fma_f32 v7, -v4, v6, 1.0
	v_fmac_f32_e32 v6, v7, v6
	v_mul_f32_e32 v7, v5, v6
	v_fma_f32 v8, -v4, v7, v5
	v_fmac_f32_e32 v7, v8, v6
	v_fma_f32 v4, -v4, v7, v5
	v_div_fmas_f32 v4, v4, v6, v7
	v_div_fixup_f32 v0, v4, v0, 1.0
	v_fmamk_f32 v2, v2, 0x3a800000, v40
	v_mul_f32_e32 v10, 0x4f800000, v2
	v_cmp_gt_f32_e32 vcc, s2, v2
	s_nop 1
	v_cndmask_b32_e32 v2, v2, v10, vcc
	v_sqrt_f32_e32 v10, v2
	s_nop 0
	v_add_u32_e32 v11, -1, v10
	v_add_u32_e32 v12, 1, v10
	v_fma_f32 v13, -v11, v10, v2
	v_fma_f32 v14, -v12, v10, v2
	v_cmp_ge_f32_e64 s[0:1], 0, v13
	s_nop 1
	v_cndmask_b32_e64 v10, v10, v11, s[0:1]
	v_cmp_lt_f32_e64 s[0:1], 0, v14
	s_nop 1
	v_cndmask_b32_e64 v10, v10, v12, s[0:1]
	v_mul_f32_e32 v11, 0x37800000, v10
	v_cndmask_b32_e32 v10, v10, v11, vcc
	v_cmp_class_f32_e32 vcc, v2, v41
	s_nop 1
	v_cndmask_b32_e32 v2, v10, v2, vcc
	v_div_scale_f32 v10, s[0:1], v2, v2, 1.0
	v_rcp_f32_e32 v12, v10
	v_div_scale_f32 v11, vcc, 1.0, v2, 1.0
	v_fma_f32 v13, -v10, v12, 1.0
	v_fmac_f32_e32 v12, v13, v12
	v_mul_f32_e32 v13, v11, v12
	v_fma_f32 v14, -v10, v13, v11
	v_fmac_f32_e32 v13, v14, v12
	v_fma_f32 v10, -v10, v13, v11
	v_div_fmas_f32 v10, v10, v12, v13
	v_div_fixup_f32 v2, v10, v2, 1.0
	v_pk_add_f32 v[210:211], v[210:211], 1.0 op_sel_hi:[1,0]
	v_pk_add_f32 v[212:213], v[212:213], 1.0 op_sel_hi:[1,0]
	v_pk_add_f32 v[214:215], v[214:215], 1.0 op_sel_hi:[1,0]
	v_pk_add_f32 v[216:217], v[216:217], 1.0 op_sel_hi:[1,0]
	v_pk_add_f32 v[218:219], v[218:219], 1.0 op_sel_hi:[1,0]
	v_pk_add_f32 v[220:221], v[220:221], 1.0 op_sel_hi:[1,0]
	v_pk_add_f32 v[222:223], v[222:223], 1.0 op_sel_hi:[1,0]
	v_pk_add_f32 v[224:225], v[224:225], 1.0 op_sel_hi:[1,0]
	v_pk_mul_f32 v[112:113], v[112:113], v[0:1] op_sel_hi:[1,0]
	v_pk_mul_f32 v[114:115], v[114:115], v[0:1] op_sel_hi:[1,0]
	v_pk_mul_f32 v[112:113], v[144:145], v[112:113]
	v_pk_mul_f32 v[114:115], v[146:147], v[114:115]
	v_pk_fma_f32 v[112:113], v[210:211], v[112:113], v[194:195]
	v_pk_fma_f32 v[114:115], v[212:213], v[114:115], v[196:197]
	v_cvt_pk_bf16_f32 v112, v112, v113
	v_cvt_pk_bf16_f32 v113, v114, v115
	global_store_dwordx2 v[30:31], v[112:113], off offset:-3584
	v_pk_mul_f32 v[116:117], v[116:117], v[0:1] op_sel_hi:[1,0]
	v_pk_mul_f32 v[118:119], v[118:119], v[0:1] op_sel_hi:[1,0]
	v_pk_mul_f32 v[116:117], v[148:149], v[116:117]
	v_pk_mul_f32 v[118:119], v[150:151], v[118:119]
	v_pk_fma_f32 v[116:117], v[214:215], v[116:117], v[198:199]
	v_pk_fma_f32 v[118:119], v[216:217], v[118:119], v[200:201]
	v_cvt_pk_bf16_f32 v116, v116, v117
	v_cvt_pk_bf16_f32 v117, v118, v119
	global_store_dwordx2 v[30:31], v[116:117], off offset:-3072
	v_pk_mul_f32 v[120:121], v[120:121], v[0:1] op_sel_hi:[1,0]
	v_pk_mul_f32 v[122:123], v[122:123], v[0:1] op_sel_hi:[1,0]
	v_pk_mul_f32 v[120:121], v[152:153], v[120:121]
	v_pk_mul_f32 v[122:123], v[154:155], v[122:123]
	v_pk_fma_f32 v[120:121], v[218:219], v[120:121], v[202:203]
	v_pk_fma_f32 v[122:123], v[220:221], v[122:123], v[204:205]
	v_cvt_pk_bf16_f32 v120, v120, v121
	v_cvt_pk_bf16_f32 v121, v122, v123
	global_store_dwordx2 v[30:31], v[120:121], off offset:-2560
	v_pk_mul_f32 v[124:125], v[124:125], v[0:1] op_sel_hi:[1,0]
	v_pk_mul_f32 v[126:127], v[126:127], v[0:1] op_sel_hi:[1,0]
	v_pk_mul_f32 v[124:125], v[156:157], v[124:125]
	v_pk_mul_f32 v[126:127], v[158:159], v[126:127]
	v_pk_fma_f32 v[124:125], v[222:223], v[124:125], v[206:207]
	v_pk_fma_f32 v[126:127], v[224:225], v[126:127], v[208:209]
	v_cvt_pk_bf16_f32 v124, v124, v125
	v_cvt_pk_bf16_f32 v125, v126, v127
	global_store_dwordx2 v[30:31], v[124:125], off offset:-2048
	v_pk_mul_f32 v[128:129], v[128:129], v[2:3] op_sel_hi:[1,0]
	v_pk_mul_f32 v[130:131], v[130:131], v[2:3] op_sel_hi:[1,0]
	v_pk_mul_f32 v[128:129], v[144:145], v[128:129]
	v_pk_mul_f32 v[130:131], v[146:147], v[130:131]
	v_pk_fma_f32 v[128:129], v[210:211], v[128:129], v[194:195]
	v_pk_fma_f32 v[130:131], v[212:213], v[130:131], v[196:197]
	v_cvt_pk_bf16_f32 v128, v128, v129
	v_cvt_pk_bf16_f32 v129, v130, v131
	global_store_dwordx2 v[30:31], v[128:129], off offset:-1536
	v_pk_mul_f32 v[132:133], v[132:133], v[2:3] op_sel_hi:[1,0]
	v_pk_mul_f32 v[134:135], v[134:135], v[2:3] op_sel_hi:[1,0]
	v_pk_mul_f32 v[132:133], v[148:149], v[132:133]
	v_pk_mul_f32 v[134:135], v[150:151], v[134:135]
	v_pk_fma_f32 v[132:133], v[214:215], v[132:133], v[198:199]
	v_pk_fma_f32 v[134:135], v[216:217], v[134:135], v[200:201]
	v_cvt_pk_bf16_f32 v132, v132, v133
	v_cvt_pk_bf16_f32 v133, v134, v135
	global_store_dwordx2 v[30:31], v[132:133], off offset:-1024
	v_pk_mul_f32 v[136:137], v[136:137], v[2:3] op_sel_hi:[1,0]
	v_pk_mul_f32 v[138:139], v[138:139], v[2:3] op_sel_hi:[1,0]
	v_pk_mul_f32 v[136:137], v[152:153], v[136:137]
	v_pk_mul_f32 v[138:139], v[154:155], v[138:139]
	v_pk_fma_f32 v[136:137], v[218:219], v[136:137], v[202:203]
	v_pk_fma_f32 v[138:139], v[220:221], v[138:139], v[204:205]
	v_cvt_pk_bf16_f32 v136, v136, v137
	v_cvt_pk_bf16_f32 v137, v138, v139
	global_store_dwordx2 v[30:31], v[136:137], off offset:-512
	v_pk_mul_f32 v[140:141], v[140:141], v[2:3] op_sel_hi:[1,0]
	v_pk_mul_f32 v[142:143], v[142:143], v[2:3] op_sel_hi:[1,0]
	v_pk_mul_f32 v[140:141], v[156:157], v[140:141]
	v_pk_mul_f32 v[142:143], v[158:159], v[142:143]
	v_pk_fma_f32 v[140:141], v[222:223], v[140:141], v[206:207]
	v_pk_fma_f32 v[142:143], v[224:225], v[142:143], v[208:209]
	v_cvt_pk_bf16_f32 v140, v140, v141
	v_cvt_pk_bf16_f32 v141, v142, v143
	global_store_dwordx2 v[30:31], v[140:141], off
	v_lshl_add_u64 v[30:31], v[30:31], 0, s[10:11]
	s_add_i32 s4, s4, s8
	s_cmp_gt_i32 s4, s101
	s_cbranch_scc0 .Lrms_loop
